# v52 plus gdn prompt-scan preamble waits only for chunk 0 DMA pieces (vmcnt 36), warm-up copies of chunks 1-2 stay in flight
# baseline (speedup 1.0000x reference)
; DI void lds_barrier() { asm volatile("s_waitcnt lgkmcnt(0)" ::: "memory"); __builtin_amdgcn_s_barrier(); asm volatile("" ::: "memory"); }
; #define GDN_DMA(n, buf) do { const unsigned char* g_ = gblk + (size_t)(n) * GOP_STRIDE; _Pragma("unroll") for (int i_ = 0; i_ < 18; ++i_) { const int pc_ = (wid - 4) + 4 * i_; \
;         __builtin_amdgcn_global_load_lds((const unsigned*)((g_ + pc_ * 1024) + voff16), (LAS unsigned*)(lds + (buf) * 73728 + pc_ * 1024), 16, 0, 0); } } while (0)
; #define GDN_BAR() do { asm volatile("" ::: "memory"); __builtin_amdgcn_s_barrier(); asm volatile("" ::: "memory"); } while (0)
; #define GDN_PF(n) do { const unsigned char* g_ = gblk + (size_t)(n) * GOP_STRIDE; _Pragma("unroll") for (int i_ = 0; i_ < 18; ++i_) { const int pc_ = (wid - 4) + 4 * i_; \
;         __builtin_amdgcn_global_load_lds((const unsigned*)((g_ + pc_ * 1024) + voff16), (LAS unsigned*)(lds + 148480 + (wid - 4) * 1024), 16, 0, 0); } } while (0)
; DI void gdn_scan_prompt(const Params& p, int bh, unsigned char* smem) {
;     ...
;     lds_barrier();
;     ...
;     if (wid >= 4) { GDN_DMA(0, 0); GDN_PF(1); GDN_PF(2); asm volatile("s_waitcnt vmcnt(0)" ::: "memory"); }
;     GDN_BAR();
.LBB0_837:
	s_andn2_b64 vcc, exec, s[0:1]
	s_ashr_i32 s21, s20, 31
	s_cbranch_vccnz .LBB0_839
	v_lshl_add_u64 v[6:7], s[28:29], 0, v[2:3]
	s_ashr_i32 s37, s36, 31
	s_add_i32 s24, s36, 0
	v_lshl_add_u64 v[8:9], v[6:7], 0, s[36:37]
	s_mov_b32 m0, s24
	s_ashr_i32 s35, s34, 31
	s_add_i32 s0, s34, 0
	s_add_i32 s38, s34, 0x1000
	global_load_lds_dwordx4 v[8:9], off
	v_lshl_add_u64 v[8:9], v[6:7], 0, s[34:35]
	s_mov_b32 m0, s0
	s_ashr_i32 s39, s38, 31
	s_add_i32 s40, s34, 0x2000
	global_load_lds_dwordx4 v[8:9], off
	v_lshl_add_u64 v[8:9], v[6:7], 0, s[38:39]
	s_add_i32 m0, s0, 0x1000
	s_ashr_i32 s41, s40, 31
	s_add_i32 s44, s34, 0x3000
	global_load_lds_dwordx4 v[8:9], off
	v_lshl_add_u64 v[8:9], v[6:7], 0, s[40:41]
	s_add_i32 m0, s0, 0x2000
	s_ashr_i32 s45, s44, 31
	s_add_i32 s46, s34, 0x4000
	global_load_lds_dwordx4 v[8:9], off
	v_lshl_add_u64 v[8:9], v[6:7], 0, s[44:45]
	s_add_i32 m0, s0, 0x3000
	s_ashr_i32 s47, s46, 31
	s_add_i32 s56, s34, 0x5000
	global_load_lds_dwordx4 v[8:9], off
	v_lshl_add_u64 v[8:9], v[6:7], 0, s[46:47]
	s_add_i32 m0, s0, 0x4000
	s_ashr_i32 s57, s56, 31
	s_add_i32 s64, s34, 0x6000
	global_load_lds_dwordx4 v[8:9], off
	v_lshl_add_u64 v[8:9], v[6:7], 0, s[56:57]
	s_add_i32 m0, s0, 0x5000
	s_ashr_i32 s65, s64, 31
	s_add_i32 s66, s34, 0x7000
	global_load_lds_dwordx4 v[8:9], off
	v_lshl_add_u64 v[8:9], v[6:7], 0, s[64:65]
	s_add_i32 m0, s0, 0x6000
	s_ashr_i32 s67, s66, 31
	s_add_i32 s72, s34, 0x8000
	global_load_lds_dwordx4 v[8:9], off
	v_lshl_add_u64 v[8:9], v[6:7], 0, s[66:67]
	s_add_i32 m0, s0, 0x7000
	s_ashr_i32 s73, s72, 31
	s_add_i32 s74, s34, 0x9000
	global_load_lds_dwordx4 v[8:9], off
	v_lshl_add_u64 v[8:9], v[6:7], 0, s[72:73]
	s_add_i32 m0, s0, 0x8000
	s_ashr_i32 s75, s74, 31
	s_add_i32 s92, s34, 0xa000
	global_load_lds_dwordx4 v[8:9], off
	v_lshl_add_u64 v[8:9], v[6:7], 0, s[74:75]
	s_add_i32 m0, s0, 0x9000
	s_ashr_i32 s93, s92, 31
	s_add_i32 s94, s34, 0xb000
	global_load_lds_dwordx4 v[8:9], off
	v_lshl_add_u64 v[8:9], v[6:7], 0, s[92:93]
	s_add_i32 m0, s0, 0xa000
	s_ashr_i32 s95, s94, 31
	s_add_i32 s96, s34, 0xc000
	global_load_lds_dwordx4 v[8:9], off
	v_lshl_add_u64 v[8:9], v[6:7], 0, s[94:95]
	s_add_i32 m0, s0, 0xb000
	s_ashr_i32 s97, s96, 31
	s_add_i32 s42, s34, 0xd000
	global_load_lds_dwordx4 v[8:9], off
	v_lshl_add_u64 v[8:9], v[6:7], 0, s[96:97]
	s_add_i32 m0, s0, 0xc000
	s_ashr_i32 s43, s42, 31
	s_add_i32 s88, s34, 0xe000
	global_load_lds_dwordx4 v[8:9], off
	v_lshl_add_u64 v[8:9], v[6:7], 0, s[42:43]
	s_add_i32 m0, s0, 0xd000
	s_ashr_i32 s89, s88, 31
	s_add_i32 s84, s34, 0xf000
	global_load_lds_dwordx4 v[8:9], off
	v_lshl_add_u64 v[8:9], v[6:7], 0, s[88:89]
	s_add_i32 m0, s0, 0xe000
	s_ashr_i32 s85, s84, 31
	s_add_i32 s6, s34, 0x10000
	global_load_lds_dwordx4 v[8:9], off
	v_lshl_add_u64 v[8:9], v[6:7], 0, s[84:85]
	s_add_i32 m0, s0, 0xf000
	s_ashr_i32 s7, s6, 31
	global_load_lds_dwordx4 v[8:9], off
	v_lshl_add_u64 v[8:9], v[6:7], 0, s[6:7]
	s_add_i32 m0, s0, 0x10000
	s_mov_b64 s[0:1], 0x12100
	global_load_lds_dwordx4 v[8:9], off
	v_lshl_add_u64 v[8:9], v[6:7], 0, s[0:1]
	s_add_i32 m0, s24, 0x24400
	v_lshl_add_u64 v[10:11], v[8:9], 0, s[36:37]
	global_load_lds_dwordx4 v[10:11], off
	v_lshl_add_u64 v[10:11], v[8:9], 0, s[34:35]
	global_load_lds_dwordx4 v[10:11], off
	v_lshl_add_u64 v[10:11], v[8:9], 0, s[38:39]
	global_load_lds_dwordx4 v[10:11], off
	v_lshl_add_u64 v[10:11], v[8:9], 0, s[40:41]
	global_load_lds_dwordx4 v[10:11], off
	v_lshl_add_u64 v[10:11], v[8:9], 0, s[44:45]
	global_load_lds_dwordx4 v[10:11], off
	v_lshl_add_u64 v[10:11], v[8:9], 0, s[46:47]
	global_load_lds_dwordx4 v[10:11], off
	v_lshl_add_u64 v[10:11], v[8:9], 0, s[56:57]
	global_load_lds_dwordx4 v[10:11], off
	v_lshl_add_u64 v[10:11], v[8:9], 0, s[64:65]
	global_load_lds_dwordx4 v[10:11], off
	v_lshl_add_u64 v[10:11], v[8:9], 0, s[66:67]
	global_load_lds_dwordx4 v[10:11], off
	v_lshl_add_u64 v[10:11], v[8:9], 0, s[72:73]
	global_load_lds_dwordx4 v[10:11], off
	v_lshl_add_u64 v[10:11], v[8:9], 0, s[74:75]
	global_load_lds_dwordx4 v[10:11], off
	v_lshl_add_u64 v[10:11], v[8:9], 0, s[92:93]
	global_load_lds_dwordx4 v[10:11], off
	v_lshl_add_u64 v[10:11], v[8:9], 0, s[94:95]
	global_load_lds_dwordx4 v[10:11], off
	v_lshl_add_u64 v[10:11], v[8:9], 0, s[96:97]
	global_load_lds_dwordx4 v[10:11], off
	v_lshl_add_u64 v[10:11], v[8:9], 0, s[42:43]
	global_load_lds_dwordx4 v[10:11], off
	v_lshl_add_u64 v[10:11], v[8:9], 0, s[88:89]
	s_mov_b64 s[0:1], 0x24200
	global_load_lds_dwordx4 v[10:11], off
	v_lshl_add_u64 v[10:11], v[8:9], 0, s[84:85]
	v_lshl_add_u64 v[8:9], v[8:9], 0, s[6:7]
	v_lshl_add_u64 v[6:7], v[6:7], 0, s[0:1]
	global_load_lds_dwordx4 v[10:11], off
	global_load_lds_dwordx4 v[8:9], off
	v_lshl_add_u64 v[8:9], v[6:7], 0, s[36:37]
	global_load_lds_dwordx4 v[8:9], off
	v_lshl_add_u64 v[8:9], v[6:7], 0, s[34:35]
	global_load_lds_dwordx4 v[8:9], off
	v_lshl_add_u64 v[8:9], v[6:7], 0, s[38:39]
	global_load_lds_dwordx4 v[8:9], off
	v_lshl_add_u64 v[8:9], v[6:7], 0, s[40:41]
	global_load_lds_dwordx4 v[8:9], off
	v_lshl_add_u64 v[8:9], v[6:7], 0, s[44:45]
	global_load_lds_dwordx4 v[8:9], off
	v_lshl_add_u64 v[8:9], v[6:7], 0, s[46:47]
	global_load_lds_dwordx4 v[8:9], off
	v_lshl_add_u64 v[8:9], v[6:7], 0, s[56:57]
	global_load_lds_dwordx4 v[8:9], off
	v_lshl_add_u64 v[8:9], v[6:7], 0, s[64:65]
	global_load_lds_dwordx4 v[8:9], off
	v_lshl_add_u64 v[8:9], v[6:7], 0, s[66:67]
	global_load_lds_dwordx4 v[8:9], off
	v_lshl_add_u64 v[8:9], v[6:7], 0, s[72:73]
	global_load_lds_dwordx4 v[8:9], off
	v_lshl_add_u64 v[8:9], v[6:7], 0, s[74:75]
	global_load_lds_dwordx4 v[8:9], off
	v_lshl_add_u64 v[8:9], v[6:7], 0, s[92:93]
	global_load_lds_dwordx4 v[8:9], off
	v_lshl_add_u64 v[8:9], v[6:7], 0, s[94:95]
	global_load_lds_dwordx4 v[8:9], off
	v_lshl_add_u64 v[8:9], v[6:7], 0, s[96:97]
	global_load_lds_dwordx4 v[8:9], off
	v_lshl_add_u64 v[8:9], v[6:7], 0, s[42:43]
	global_load_lds_dwordx4 v[8:9], off
	v_lshl_add_u64 v[8:9], v[6:7], 0, s[88:89]
	global_load_lds_dwordx4 v[8:9], off
	v_lshl_add_u64 v[8:9], v[6:7], 0, s[84:85]
	v_lshl_add_u64 v[6:7], v[6:7], 0, s[6:7]
	global_load_lds_dwordx4 v[8:9], off
	global_load_lds_dwordx4 v[6:7], off
	s_waitcnt vmcnt(36)
